# S5 chain: Z tile handed to the scan through LDS (swizzled), hand-written scan on waves 0/1 reading LDS; F32Z global stores and their drain removed
# baseline (speedup 1.0000x reference)
.LBB0_278:
	s_cmpk_eq_i32 s33, 0x100
	s_cbranch_scc1 .Lz_keep
	v_ashrrev_i32_e32 v169, 31, v168
	s_lshl_b32 s6, s22, 8
	v_lshlrev_b64 v[128:129], 10, v[168:169]
	s_ashr_i32 s7, s6, 31
	v_lshl_add_u64 v[128:129], s[10:11], 0, v[128:129]
	s_lshl_b64 s[6:7], s[6:7], 2
	v_lshl_add_u64 v[128:129], v[128:129], 0, s[6:7]
	s_lshl_b32 s42, s81, 2
	s_mov_b32 s43, s27
	v_lshl_add_u64 v[128:129], v[128:129], 0, s[42:43]
	v_lshlrev_b32_e32 v144, 2, v154
	v_lshl_add_u64 v[128:129], v[128:129], 0, v[144:145]
	global_store_dwordx4 v[128:129], v[124:127], off
	global_store_dwordx4 v[128:129], v[120:123], off offset:16
	s_nop 1
	v_or_b32_e32 v104, 16, v168
	v_ashrrev_i32_e32 v105, 31, v104
	v_lshlrev_b64 v[104:105], 10, v[104:105]
	v_lshl_add_u64 v[104:105], s[10:11], 0, v[104:105]
	v_lshl_add_u64 v[104:105], v[104:105], 0, s[6:7]
	v_lshl_add_u64 v[104:105], v[104:105], 0, s[42:43]
	v_lshl_add_u64 v[104:105], v[104:105], 0, v[144:145]
	global_store_dwordx4 v[104:105], v[116:119], off
	global_store_dwordx4 v[104:105], v[112:115], off offset:16
	s_nop 1
	v_or_b32_e32 v88, 32, v168
	v_ashrrev_i32_e32 v89, 31, v88
	v_lshlrev_b64 v[88:89], 10, v[88:89]
	v_lshl_add_u64 v[88:89], s[10:11], 0, v[88:89]
	v_lshl_add_u64 v[88:89], v[88:89], 0, s[6:7]
	v_lshl_add_u64 v[88:89], v[88:89], 0, s[42:43]
	v_lshl_add_u64 v[88:89], v[88:89], 0, v[144:145]
	global_store_dwordx4 v[88:89], v[100:103], off
	global_store_dwordx4 v[88:89], v[96:99], off offset:16
	s_nop 1
	v_or_b32_e32 v72, 48, v168
	v_ashrrev_i32_e32 v73, 31, v72
	v_lshlrev_b64 v[72:73], 10, v[72:73]
	v_lshl_add_u64 v[72:73], s[10:11], 0, v[72:73]
	v_lshl_add_u64 v[72:73], v[72:73], 0, s[6:7]
	v_lshl_add_u64 v[72:73], v[72:73], 0, s[42:43]
	v_lshl_add_u64 v[72:73], v[72:73], 0, v[144:145]
	global_store_dwordx4 v[72:73], v[84:87], off
	global_store_dwordx4 v[72:73], v[80:83], off offset:16
	s_mov_b64 s[6:7], 0x20000
	s_nop 0
	v_add_co_u32_e32 v66, vcc, s95, v128
	v_lshl_add_u64 v[64:65], v[128:129], 0, s[6:7]
	s_nop 0
	v_addc_co_u32_e32 v67, vcc, 0, v129, vcc
	global_store_dwordx4 v[66:67], v[60:63], off
	global_store_dwordx4 v[64:65], v[56:59], off offset:16
	s_mov_b64 s[6:7], 0x24000
	s_nop 0
	v_add_co_u32_e32 v42, vcc, s67, v128
	v_lshl_add_u64 v[40:41], v[128:129], 0, s[6:7]
	s_nop 0
	v_addc_co_u32_e32 v43, vcc, 0, v129, vcc
	global_store_dwordx4 v[42:43], v[52:55], off
	global_store_dwordx4 v[40:41], v[48:51], off offset:16
	s_mov_b64 s[6:7], 0x28000
	s_nop 0
	v_add_co_u32_e32 v26, vcc, 0x28000, v128
	v_lshl_add_u64 v[24:25], v[128:129], 0, s[6:7]
	s_nop 0
	v_addc_co_u32_e32 v27, vcc, 0, v129, vcc
	global_store_dwordx4 v[26:27], v[36:39], off
	global_store_dwordx4 v[24:25], v[32:35], off offset:16
	s_mov_b64 s[6:7], 0x2c000
	s_nop 0
	v_add_co_u32_e32 v10, vcc, 0x2c000, v128
	v_lshl_add_u64 v[8:9], v[128:129], 0, s[6:7]
	s_nop 0
	v_addc_co_u32_e32 v11, vcc, 0, v129, vcc
	global_store_dwordx4 v[10:11], v[20:23], off
	global_store_dwordx4 v[8:9], v[16:19], off offset:16
.Lz_keep:
	s_and_b64 vcc, exec, s[4:5]
	s_mov_b64 s[4:5], -1
	s_cbranch_vccnz .LBB0_227
	s_branch .LBB0_363

.LBB0_366:
	s_cmp_lg_u32 s19, 0
	s_cselect_b64 s[0:1], -1, 0
	s_xor_b64 s[4:5], s[38:39], -1
	s_or_b64 s[0:1], s[4:5], s[0:1]
	s_and_b64 vcc, exec, s[0:1]
	s_cbranch_vccnz .LBB0_192
	s_cmpk_lg_i32 s33, 0x100
	s_cbranch_scc1 .Lzs_orig
	s_cmp_lt_u32 s52, 64
	s_cbranch_scc0 .LBB0_191
	v_and_b32_e32 v130, 63, v244
	v_lshrrev_b32_e32 v131, 6, v244
	v_and_b32_e32 v132, 15, v130
	v_lshrrev_b32_e32 v133, 4, v130
	v_readfirstlane_b32 s0, v131
	v_readfirstlane_b32 s5, v168
	v_mul_u32_u24_e32 v138, 0x88, v130
	s_lshr_b32 s5, s5, 8
	s_add_i32 s6, s44, -2
	s_mul_i32 s7, s6, 47
	s_lshr_b32 s7, s7, 9
	s_mul_i32 s7, s7, 0x22000
	s_lshr_b32 s6, s5, 2
	s_mul_i32 s6, s6, 0x2200
	s_add_i32 s6, s6, s7
	s_add_i32 s6, s6, 0xdc00080
	s_add_u32 s6, s78, s6
	s_addc_u32 s7, s79, 0
	global_load_dwordx2 v[74:75], v138, s[6:7]
	s_lshr_b32 s1, s0, 2
	s_and_b32 s4, s0, 3
	s_lshl_b32 s1, s1, 15
	s_lshl_b32 s4, s4, 7
	v_lshlrev_b32_e32 v134, 9, v132
	v_lshl_add_u32 v135, v133, 5, s4
	v_and_b32_e32 v136, 7, v132
	v_lshlrev_b32_e32 v136, 4, v136
	v_xor_b32_e32 v135, v135, v136
	v_add3_u32 v134, v134, v135, s1
	v_xor_b32_e32 v135, 16, v134
	v_add_u32_e32 v136, 0x10000, v134
	v_add_u32_e32 v137, 0x10000, v135
	ds_write_b128 v134, v[124:127]
	ds_write_b128 v135, v[120:123]
	ds_write_b128 v134, v[116:119] offset:8192
	ds_write_b128 v135, v[112:115] offset:8192
	ds_write_b128 v134, v[100:103] offset:16384
	ds_write_b128 v135, v[96:99] offset:16384
	ds_write_b128 v134, v[84:87] offset:24576
	ds_write_b128 v135, v[80:83] offset:24576
	ds_write_b128 v136, v[60:63]
	ds_write_b128 v137, v[56:59]
	ds_write_b128 v136, v[52:55] offset:8192
	ds_write_b128 v137, v[48:51] offset:8192
	ds_write_b128 v136, v[36:39] offset:16384
	ds_write_b128 v137, v[32:35] offset:16384
	ds_write_b128 v136, v[20:23] offset:24576
	ds_write_b128 v137, v[16:19] offset:24576
	s_waitcnt lgkmcnt(0)
	s_barrier
	s_cmp_gt_u32 s0, 1
	s_cbranch_scc1 .LBB0_191
	s_lshl_b32 s8, s5, 8
	s_lshl_b32 s9, s0, 7
	s_add_i32 s8, s8, s9
	s_mul_i32 s8, s8, 0x300
	s_add_u32 s8, s78, s8
	s_addc_u32 s9, s79, 0
	s_add_u32 s8, s8, 0x22000000
	s_addc_u32 s9, s9, 0
	v_lshlrev_b32_e32 v76, 2, v130
	v_add_u32_e32 v76, 0x200, v76
	v_lshlrev_b32_e32 v81, 3, v130
	s_lshl_b32 s4, s0, 16
	v_xor_b32_e32 v64, 0, v81
	v_xor_b32_e32 v65, 16, v81
	v_xor_b32_e32 v66, 32, v81
	v_xor_b32_e32 v67, 48, v81
	v_xor_b32_e32 v68, 64, v81
	v_xor_b32_e32 v69, 0x50, v81
	v_xor_b32_e32 v70, 0x60, v81
	v_xor_b32_e32 v71, 0x70, v81
	v_add_u32_e32 v64, s4, v64
	v_add_u32_e32 v65, s4, v65
	v_add_u32_e32 v66, s4, v66
	v_add_u32_e32 v67, s4, v67
	v_add_u32_e32 v68, s4, v68
	v_add_u32_e32 v69, s4, v69
	v_add_u32_e32 v70, s4, v70
	v_add_u32_e32 v71, s4, v71
	v_mov_b32_e32 v72, 0
	v_mov_b32_e32 v73, 0
	ds_read_b64 v[0:1], v64 offset:0
	ds_read_b64 v[2:3], v65 offset:512
	ds_read_b64 v[4:5], v66 offset:1024
	ds_read_b64 v[6:7], v67 offset:1536
	ds_read_b64 v[8:9], v68 offset:2048
	ds_read_b64 v[10:11], v69 offset:2560
	ds_read_b64 v[12:13], v70 offset:3072
	ds_read_b64 v[14:15], v71 offset:3584
	s_mov_b32 s4, 0
	s_waitcnt vmcnt(0)
.Lzs_loop:
	ds_read_b64 v[16:17], v64 offset:4096
	ds_read_b64 v[18:19], v65 offset:4608
	ds_read_b64 v[20:21], v66 offset:5120
	ds_read_b64 v[22:23], v67 offset:5632
	ds_read_b64 v[24:25], v68 offset:6144
	ds_read_b64 v[26:27], v69 offset:6656
	ds_read_b64 v[28:29], v70 offset:7168
	ds_read_b64 v[30:31], v71 offset:7680
	s_waitcnt lgkmcnt(8)
	v_cvt_pk_bf16_f32 v77, v72, v73
	global_store_dword v76, v77, s[8:9]
	s_add_u32 s8, s8, 0x300
	s_addc_u32 s9, s9, 0
	v_fma_f32 v78, -v75, v73, v0
	v_fma_f32 v79, v75, v72, v1
	v_fma_f32 v78, v74, v72, v78
	v_fma_f32 v79, v74, v73, v79
	v_cvt_pk_bf16_f32 v77, v78, v79
	global_store_dword v76, v77, s[8:9]
	s_add_u32 s8, s8, 0x300
	s_addc_u32 s9, s9, 0
	v_fma_f32 v72, -v75, v79, v2
	v_fma_f32 v73, v75, v78, v3
	v_fma_f32 v72, v74, v78, v72
	v_fma_f32 v73, v74, v79, v73
	v_cvt_pk_bf16_f32 v77, v72, v73
	global_store_dword v76, v77, s[8:9]
	s_add_u32 s8, s8, 0x300
	s_addc_u32 s9, s9, 0
	v_fma_f32 v78, -v75, v73, v4
	v_fma_f32 v79, v75, v72, v5
	v_fma_f32 v78, v74, v72, v78
	v_fma_f32 v79, v74, v73, v79
	v_cvt_pk_bf16_f32 v77, v78, v79
	global_store_dword v76, v77, s[8:9]
	s_add_u32 s8, s8, 0x300
	s_addc_u32 s9, s9, 0
	v_fma_f32 v72, -v75, v79, v6
	v_fma_f32 v73, v75, v78, v7
	v_fma_f32 v72, v74, v78, v72
	v_fma_f32 v73, v74, v79, v73
	v_cvt_pk_bf16_f32 v77, v72, v73
	global_store_dword v76, v77, s[8:9]
	s_add_u32 s8, s8, 0x300
	s_addc_u32 s9, s9, 0
	v_fma_f32 v78, -v75, v73, v8
	v_fma_f32 v79, v75, v72, v9
	v_fma_f32 v78, v74, v72, v78
	v_fma_f32 v79, v74, v73, v79
	v_cvt_pk_bf16_f32 v77, v78, v79
	global_store_dword v76, v77, s[8:9]
	s_add_u32 s8, s8, 0x300
	s_addc_u32 s9, s9, 0
	v_fma_f32 v72, -v75, v79, v10
	v_fma_f32 v73, v75, v78, v11
	v_fma_f32 v72, v74, v78, v72
	v_fma_f32 v73, v74, v79, v73
	v_cvt_pk_bf16_f32 v77, v72, v73
	global_store_dword v76, v77, s[8:9]
	s_add_u32 s8, s8, 0x300
	s_addc_u32 s9, s9, 0
	v_fma_f32 v78, -v75, v73, v12
	v_fma_f32 v79, v75, v72, v13
	v_fma_f32 v78, v74, v72, v78
	v_fma_f32 v79, v74, v73, v79
	v_cvt_pk_bf16_f32 v77, v78, v79
	global_store_dword v76, v77, s[8:9]
	s_add_u32 s8, s8, 0x300
	s_addc_u32 s9, s9, 0
	v_fma_f32 v72, -v75, v79, v14
	v_fma_f32 v73, v75, v78, v15
	v_fma_f32 v72, v74, v78, v72
	v_fma_f32 v73, v74, v79, v73
	v_add_u32_e32 v64, 0x2000, v64
	v_add_u32_e32 v65, 0x2000, v65
	v_add_u32_e32 v66, 0x2000, v66
	v_add_u32_e32 v67, 0x2000, v67
	v_add_u32_e32 v68, 0x2000, v68
	v_add_u32_e32 v69, 0x2000, v69
	v_add_u32_e32 v70, 0x2000, v70
	v_add_u32_e32 v71, 0x2000, v71
	ds_read_b64 v[0:1], v64 offset:0
	ds_read_b64 v[2:3], v65 offset:512
	ds_read_b64 v[4:5], v66 offset:1024
	ds_read_b64 v[6:7], v67 offset:1536
	ds_read_b64 v[8:9], v68 offset:2048
	ds_read_b64 v[10:11], v69 offset:2560
	ds_read_b64 v[12:13], v70 offset:3072
	ds_read_b64 v[14:15], v71 offset:3584
	s_waitcnt lgkmcnt(8)
	v_cvt_pk_bf16_f32 v77, v72, v73
	global_store_dword v76, v77, s[8:9]
	s_add_u32 s8, s8, 0x300
	s_addc_u32 s9, s9, 0
	v_fma_f32 v78, -v75, v73, v16
	v_fma_f32 v79, v75, v72, v17
	v_fma_f32 v78, v74, v72, v78
	v_fma_f32 v79, v74, v73, v79
	v_cvt_pk_bf16_f32 v77, v78, v79
	global_store_dword v76, v77, s[8:9]
	s_add_u32 s8, s8, 0x300
	s_addc_u32 s9, s9, 0
	v_fma_f32 v72, -v75, v79, v18
	v_fma_f32 v73, v75, v78, v19
	v_fma_f32 v72, v74, v78, v72
	v_fma_f32 v73, v74, v79, v73
	v_cvt_pk_bf16_f32 v77, v72, v73
	global_store_dword v76, v77, s[8:9]
	s_add_u32 s8, s8, 0x300
	s_addc_u32 s9, s9, 0
	v_fma_f32 v78, -v75, v73, v20
	v_fma_f32 v79, v75, v72, v21
	v_fma_f32 v78, v74, v72, v78
	v_fma_f32 v79, v74, v73, v79
	v_cvt_pk_bf16_f32 v77, v78, v79
	global_store_dword v76, v77, s[8:9]
	s_add_u32 s8, s8, 0x300
	s_addc_u32 s9, s9, 0
	v_fma_f32 v72, -v75, v79, v22
	v_fma_f32 v73, v75, v78, v23
	v_fma_f32 v72, v74, v78, v72
	v_fma_f32 v73, v74, v79, v73
	v_cvt_pk_bf16_f32 v77, v72, v73
	global_store_dword v76, v77, s[8:9]
	s_add_u32 s8, s8, 0x300
	s_addc_u32 s9, s9, 0
	v_fma_f32 v78, -v75, v73, v24
	v_fma_f32 v79, v75, v72, v25
	v_fma_f32 v78, v74, v72, v78
	v_fma_f32 v79, v74, v73, v79
	v_cvt_pk_bf16_f32 v77, v78, v79
	global_store_dword v76, v77, s[8:9]
	s_add_u32 s8, s8, 0x300
	s_addc_u32 s9, s9, 0
	v_fma_f32 v72, -v75, v79, v26
	v_fma_f32 v73, v75, v78, v27
	v_fma_f32 v72, v74, v78, v72
	v_fma_f32 v73, v74, v79, v73
	v_cvt_pk_bf16_f32 v77, v72, v73
	global_store_dword v76, v77, s[8:9]
	s_add_u32 s8, s8, 0x300
	s_addc_u32 s9, s9, 0
	v_fma_f32 v78, -v75, v73, v28
	v_fma_f32 v79, v75, v72, v29
	v_fma_f32 v78, v74, v72, v78
	v_fma_f32 v79, v74, v73, v79
	v_cvt_pk_bf16_f32 v77, v78, v79
	global_store_dword v76, v77, s[8:9]
	s_add_u32 s8, s8, 0x300
	s_addc_u32 s9, s9, 0
	v_fma_f32 v72, -v75, v79, v30
	v_fma_f32 v73, v75, v78, v31
	v_fma_f32 v72, v74, v78, v72
	v_fma_f32 v73, v74, v79, v73
	s_add_i32 s4, s4, 1
	s_cmp_lg_u32 s4, 8
	s_cbranch_scc1 .Lzs_loop
	s_branch .LBB0_191
.Lzs_orig:
	v_mov_b32_e32 v1, v244
	s_ashr_i32 s7, s80, 31
	v_and_b32_e32 v0, 63, v1
	v_readfirstlane_b32 s0, v1
	v_cvt_f32_u32_e32 v1, s12
	s_ashr_i32 s6, s0, 6
	s_lshl_b32 s0, s6, 7
	s_and_b32 s9, s0, 0x80
	v_rcp_iflag_f32_e32 v1, v1
	s_sub_i32 s0, 0, s12
	v_lshlrev_b32_e32 v144, 3, v0
	s_mov_b32 s35, s27
	v_mul_f32_e32 v1, 0x4f7ffffe, v1
	v_cvt_u32_f32_e32 v1, v1
	s_lshr_b32 s8, s34, 3
	v_lshl_add_u64 v[2:3], s[10:11], 0, v[144:145]
	s_mov_b32 s14, 0
	v_readfirstlane_b32 s1, v1
	s_mul_i32 s0, s0, s1
	s_mul_hi_u32 s0, s1, s0
	s_add_i32 s15, s1, s0
	v_lshlrev_b32_e32 v4, 2, v0
	s_branch .LBB0_370
